# gla scan worker: per-tile state decay interleaved with the state-update MFMAs, two rounds of decay factors in flight
# baseline (speedup 1.0000x reference)
; #define LAS __attribute__((address_space(3)))
; #define SBAR __builtin_amdgcn_sched_barrier(0)
; #define RD_K(F, s4) do { F[0] = GK(s4, 0); F[1] = GK(s4, 1); F[2] = GK(s4, 2); F[3] = GK(s4, 3); } while (0)
; #define MM_K(F, s4) do { _Pragma("unroll") for (int T = 0; T < 4; ++T) S[T] = __builtin_amdgcn_mfma_f32_32x32x16_bf16(F[T], vf[s4], S[T], 0, 0, 0); } while (0)
; #define SBAR __builtin_amdgcn_sched_barrier(0)
; __device__ __forceinline__ void gla_scan(LAS unsigned char* lds, const bf16_t* QPimg, const bf16_t* KTimg, const bf16_t* Aimg, const bf16_t* VTimg, const bf16_t* VTmeta,
;                                          const float* dec, bf16_t* Oraw) {
;     ...
; #pragma unroll
;             for (int T = 0; T < 4; ++T)
; #pragma unroll
;                 for (int g4 = 0; g4 < 4; ++g4) { const f32x4 d4 = *(const LAS f32x4*)(st + GS_DEC + (32 * T + 8 * g4 + 4 * hi) * 4);
;                     S[T][4 * g4] *= d4.x; S[T][4 * g4 + 1] *= d4.y; S[T][4 * g4 + 2] *= d4.z; S[T][4 * g4 + 3] *= d4.w; }
;             SBAR; RD_K(fc, 2); SBAR; MM_K(fa, 0); SBAR; RD_K(fa, 3); SBAR; MM_K(fb, 1); SBAR; MM_K(fc, 2); SBAR; MM_K(fa, 3);
.LBB0_387:
	s_nop 8
	v_add_u32_e32 v238, s14, v169
	s_nop 0
	ds_read_b128 v[82:85], v238 offset:49152
	ds_read_b128 v[86:89], v238 offset:49184
	ds_read_b128 v[90:93], v238 offset:49216
	ds_read_b128 v[94:97], v238 offset:49248
	ds_read_b128 v[98:101], v238 offset:49280
	ds_read_b128 v[102:105], v238 offset:49312
	ds_read_b128 v[106:109], v238 offset:49344
	ds_read_b128 v[110:113], v238 offset:49376
	s_waitcnt lgkmcnt(4)
	v_pk_mul_f32 v[20:21], v[20:21], v[84:85]
	v_pk_mul_f32 v[22:23], v[22:23], v[86:87]
	v_pk_mul_f32 v[26:27], v[26:27], v[90:91]
	v_pk_mul_f32 v[30:31], v[30:31], v[94:95]
	v_pk_mul_f32 v[32:33], v[32:33], v[96:97]
	v_pk_mul_f32 v[28:29], v[28:29], v[92:93]
	v_pk_mul_f32 v[24:25], v[24:25], v[88:89]
	v_pk_mul_f32 v[18:19], v[18:19], v[82:83]
	ds_read_b128 v[82:85], v238 offset:49408
	ds_read_b128 v[86:89], v238 offset:49440
	ds_read_b128 v[90:93], v238 offset:49472
	ds_read_b128 v[94:97], v238 offset:49504
	v_mfma_f32_32x32x16_bf16 v[18:33], v[146:149], v[118:121], v[18:33]
	s_waitcnt lgkmcnt(4)
	v_pk_mul_f32 v[36:37], v[36:37], v[100:101]
	v_pk_mul_f32 v[38:39], v[38:39], v[102:103]
	v_pk_mul_f32 v[42:43], v[42:43], v[106:107]
	v_pk_mul_f32 v[46:47], v[46:47], v[110:111]
	v_pk_mul_f32 v[48:49], v[48:49], v[112:113]
	v_pk_mul_f32 v[44:45], v[44:45], v[108:109]
	v_pk_mul_f32 v[40:41], v[40:41], v[104:105]
	v_pk_mul_f32 v[34:35], v[34:35], v[98:99]
	ds_read_b128 v[98:101], v238 offset:49536
	ds_read_b128 v[102:105], v238 offset:49568
	ds_read_b128 v[106:109], v238 offset:49600
	ds_read_b128 v[110:113], v238 offset:49632
	v_mfma_f32_32x32x16_bf16 v[34:49], v[138:141], v[118:121], v[34:49]
	s_waitcnt lgkmcnt(4)
	v_pk_mul_f32 v[52:53], v[52:53], v[84:85]
	v_pk_mul_f32 v[54:55], v[54:55], v[86:87]
	v_pk_mul_f32 v[58:59], v[58:59], v[90:91]
	v_pk_mul_f32 v[62:63], v[62:63], v[94:95]
	v_pk_mul_f32 v[64:65], v[64:65], v[96:97]
	v_pk_mul_f32 v[60:61], v[60:61], v[92:93]
	v_pk_mul_f32 v[56:57], v[56:57], v[88:89]
	v_pk_mul_f32 v[50:51], v[50:51], v[82:83]
	v_add3_u32 v94, s14, v170, v162
	ds_read_b128 v[82:85], v94 offset:16384
	ds_read_b128 v[86:89], v94 offset:16896
	ds_read_b128 v[90:93], v94 offset:17408
	ds_read_b128 v[94:97], v94 offset:17920
	v_mfma_f32_32x32x16_bf16 v[50:65], v[130:133], v[118:121], v[50:65]
	s_waitcnt lgkmcnt(4)
	v_pk_mul_f32 v[68:69], v[68:69], v[100:101]
	v_pk_mul_f32 v[70:71], v[70:71], v[102:103]
	v_pk_mul_f32 v[74:75], v[74:75], v[106:107]
	v_pk_mul_f32 v[78:79], v[78:79], v[110:111]
	v_pk_mul_f32 v[80:81], v[80:81], v[112:113]
	v_pk_mul_f32 v[76:77], v[76:77], v[108:109]
	v_pk_mul_f32 v[72:73], v[72:73], v[104:105]
	v_pk_mul_f32 v[66:67], v[66:67], v[98:99]
	v_add3_u32 v110, s14, v171, v162
	ds_read_b128 v[98:101], v110 offset:16384
	ds_read_b128 v[102:105], v110 offset:16896
	ds_read_b128 v[106:109], v110 offset:17408
	ds_read_b128 v[110:113], v110 offset:17920
	v_mfma_f32_32x32x16_bf16 v[66:81], v[122:125], v[118:121], v[66:81]
	v_mfma_f32_32x32x16_bf16 v[18:33], v[150:153], v[10:13], v[18:33]
	v_mfma_f32_32x32x16_bf16 v[34:49], v[142:145], v[10:13], v[34:49]
	v_mfma_f32_32x32x16_bf16 v[50:65], v[134:137], v[10:13], v[50:65]
	v_mfma_f32_32x32x16_bf16 v[66:81], v[126:129], v[10:13], v[66:81]
	s_waitcnt lgkmcnt(7)
	v_mfma_f32_32x32x16_bf16 v[18:33], v[82:85], v[6:9], v[18:33]
	s_waitcnt lgkmcnt(6)
	v_mfma_f32_32x32x16_bf16 v[34:49], v[86:89], v[6:9], v[34:49]
	s_waitcnt lgkmcnt(5)
	v_mfma_f32_32x32x16_bf16 v[50:65], v[90:93], v[6:9], v[50:65]
	s_waitcnt lgkmcnt(4)
	v_mfma_f32_32x32x16_bf16 v[66:81], v[94:97], v[6:9], v[66:81]
	s_waitcnt lgkmcnt(3)
	v_mfma_f32_32x32x16_bf16 v[18:33], v[98:101], v[2:5], v[18:33]
	s_waitcnt lgkmcnt(2)
	v_mfma_f32_32x32x16_bf16 v[34:49], v[102:105], v[2:5], v[34:49]
	s_waitcnt lgkmcnt(1)
	v_mfma_f32_32x32x16_bf16 v[50:65], v[106:109], v[2:5], v[50:65]
	s_waitcnt lgkmcnt(0)
	v_mfma_f32_32x32x16_bf16 v[66:81], v[110:113], v[2:5], v[66:81]
	s_mov_b64 s[14:15], -1
	s_and_b64 vcc, exec, s[8:9]
	s_cbranch_vccz .LBB0_366
